# dilated-combine units: all 12 loads of both halves issued up front (one round trip per unit instead of six)
# speedup vs baseline: 1.0088x; 1.0027x over previous
; DI int tidx() { int t = __builtin_amdgcn_workitem_id_x(); asm volatile("" : "+v"(t)); return t; }
; DI unsigned pk2(float a, float b) { f32x2 v = {a, b}; bf2_t r = __builtin_convertvector(v, bf2_t); return __builtin_bit_cast(unsigned, r); }
; DI float bflo(unsigned u) { return __uint_as_float(u << 16); }
; DI float bfhi(unsigned u) { return __uint_as_float(u & 0xffff0000u); }
; DI void dcombine_unit(const Params& p, int u) {
;     ...
;     const int idx = u * 1024 + e * 512 + tidx(), token = idx >> 5, rem = idx & 31, h = rem >> 3, dc = rem & 7;
;     float ls[3], mx = -1e30f;
; #pragma unroll
;     for (int n = 0; n < 3; ++n) { ls[n] = p.dlse[((size_t)n * NTOK + token) * 4 + h]; mx = fmaxf(mx, ls[n]); }
;     float w[3], ws = 0.f;
; #pragma unroll
;     for (int n = 0; n < 3; ++n) { w[n] = exp2f(ls[n] - mx); ws += w[n]; }
;     const float inv = 1.f / ws;
;     float o[8];
; #pragma unroll
;     for (int i = 0; i < 8; ++i) o[i] = 0.f;
; #pragma unroll
;     for (int n = 0; n < 3; ++n) { const u32x4 d = *(const u32x4*)(p.dpart + ((size_t)n * NTOK + token) * 256 + h * 64 + dc * 8); const float wn = w[n] * inv;
; #pragma unroll
;       for (int i = 0; i < 4; ++i) { o[2 * i] += wn * bflo(d[i]); o[2 * i + 1] += wn * bfhi(d[i]); } }
;     u32x4 r = {pk2(o[0], o[1]), pk2(o[2], o[3]), pk2(o[4], o[5]), pk2(o[6], o[7])};
;     *(u32x4*)(p.Y + (size_t)token * DM + 768 + h * 64 + dc * 8) = r;
.LBB0_642:
	s_andn2_b64 vcc, exec, s[0:1]
	s_cbranch_vccnz .LBB0_574
	s_lshl_b32 s0, s96, 10
	s_add_i32 s1, s0, 0xffe00000
	v_mov_b32_e32 v4, v206
	v_readlane_b32 s52, v252, 17
	v_add_u32_e32 v0, s1, v4
	v_ashrrev_i32_e32 v8, 5, v0
	v_bfe_u32 v5, v4, 3, 2
	v_ashrrev_i32_e32 v9, 31, v8
	v_readlane_b32 s66, v252, 31
	v_readlane_b32 s67, v252, 32
	v_lshlrev_b32_e32 v112, 2, v5
	v_mov_b32_e32 v11, v113
	v_lshl_add_u64 v[0:1], v[8:9], 4, s[66:67]
	v_lshl_add_u64 v[0:1], v[0:1], 0, v[112:113]
	global_load_dword v6, v[0:1], off
	v_lshlrev_b64 v[216:217], 9, v[8:9]
	v_lshl_add_u64 v[216:217], s[94:95], 0, v[216:217]
	v_lshlrev_b32_e32 v218, 7, v5
	v_lshlrev_b32_e32 v219, 4, v4
	v_and_b32_e32 v219, 0x70, v219
	v_add_u32_e32 v218, v218, v219
	v_mov_b32_e32 v219, 0
	v_lshl_add_u64 v[216:217], v[216:217], 0, v[218:219]
	v_mov_b32_e32 v218, s30
	v_lshl_add_u64 v[220:221], v[216:217], 0, v[218:219]
	v_mov_b32_e32 v218, s31
	v_lshl_add_u64 v[222:223], v[216:217], 0, v[218:219]
	global_load_dwordx4 v[182:185], v[216:217], off
	global_load_dwordx4 v[186:189], v[220:221], off
	global_load_dwordx4 v[190:193], v[222:223], off
	v_mov_b32_e32 v218, 0x2000
	v_lshl_add_u64 v[216:217], v[216:217], 0, v[218:219]
	v_lshl_add_u64 v[220:221], v[220:221], 0, v[218:219]
	v_lshl_add_u64 v[222:223], v[222:223], 0, v[218:219]
	global_load_dwordx4 v[194:197], v[216:217], off
	global_load_dwordx4 v[198:201], v[220:221], off
	global_load_dwordx4 v[202:205], v[222:223], off
	v_mov_b32_e32 v218, s27
	v_lshl_add_u64 v[224:225], v[0:1], 0, v[218:219]
	v_mov_b32_e32 v218, s28
	v_lshl_add_u64 v[226:227], v[0:1], 0, v[218:219]
	global_load_dword v210, v[224:225], off
	global_load_dword v211, v[226:227], off
	global_load_dword v212, v[0:1], off offset:256
	global_load_dword v213, v[224:225], off offset:256
	global_load_dword v214, v[226:227], off offset:256
	v_lshlrev_b32_e32 v112, 7, v5
	v_readlane_b32 s36, v252, 36
	v_readlane_b32 s40, v252, 40
	v_readlane_b32 s41, v252, 41
	s_add_i32 s0, s0, 0xffe00200
	v_readlane_b32 s53, v252, 18
	v_readlane_b32 s54, v252, 19
	v_readlane_b32 s55, v252, 20
	v_readlane_b32 s56, v252, 21
	v_readlane_b32 s57, v252, 22
	v_readlane_b32 s58, v252, 23
	v_readlane_b32 s59, v252, 24
	v_readlane_b32 s60, v252, 25
	v_readlane_b32 s61, v252, 26
	v_readlane_b32 s62, v252, 27
	v_readlane_b32 s63, v252, 28
	v_readlane_b32 s64, v252, 29
	v_readlane_b32 s65, v252, 30
	v_readlane_b32 s37, v252, 37
	v_readlane_b32 s38, v252, 38
	v_readlane_b32 s39, v252, 39
	v_readlane_b32 s42, v252, 42
	v_readlane_b32 s43, v252, 43
	s_waitcnt vmcnt(0)
	v_max_f32_e32 v2, v6, v6
	v_max_f32_e32 v7, 0xf149f2ca, v2
	v_add_co_u32_e32 v2, vcc, s27, v0
	s_nop 1
	v_addc_co_u32_e32 v3, vcc, 0, v1, vcc
	v_add_co_u32_e32 v0, vcc, s28, v0
	v_mov_b32_e32 v2, v210
	s_nop 0
	v_addc_co_u32_e32 v1, vcc, 0, v1, vcc
	v_mov_b32_e32 v0, v211
	s_waitcnt vmcnt(0)
	v_max3_f32 v1, v7, v2, v0
	v_sub_f32_e32 v3, v6, v1
	v_cmp_gt_f32_e32 vcc, s29, v3
	v_sub_f32_e32 v2, v2, v1
	v_sub_f32_e32 v0, v0, v1
	v_cndmask_b32_e32 v6, 0, v169, vcc
	v_add_f32_e32 v3, v3, v6
	v_exp_f32_e32 v3, v3
	v_cndmask_b32_e32 v6, 0, v171, vcc
	v_cmp_gt_f32_e32 vcc, s29, v2
	v_ldexp_f32 v3, v3, v6
	s_nop 0
	v_cndmask_b32_e32 v6, 0, v169, vcc
	v_add_f32_e32 v2, v2, v6
	v_cndmask_b32_e32 v6, 0, v171, vcc
	v_cmp_gt_f32_e32 vcc, s29, v0
	v_exp_f32_e32 v2, v2
	s_nop 0
	v_cndmask_b32_e32 v1, 0, v169, vcc
	v_add_f32_e32 v0, v0, v1
	v_exp_f32_e32 v0, v0
	v_ldexp_f32 v12, v2, v6
	v_cndmask_b32_e32 v1, 0, v171, vcc
	v_ldexp_f32 v13, v0, v1
	v_add_f32_e32 v0, v3, v12
	v_add_f32_e32 v0, v13, v0
	v_div_scale_f32 v1, s[50:51], v0, v0, 1.0
	v_rcp_f32_e32 v2, v1
	s_nop 0
	v_fma_f32 v6, -v1, v2, 1.0
	v_fmac_f32_e32 v2, v6, v2
	v_div_scale_f32 v6, vcc, 1.0, v0, 1.0
	v_mul_f32_e32 v7, v6, v2
	v_fma_f32 v10, -v1, v7, v6
	v_fmac_f32_e32 v7, v10, v2
	v_fma_f32 v1, -v1, v7, v6
	v_div_fmas_f32 v1, v1, v2, v7
	v_div_fixup_f32 v14, v1, v0, 1.0
	v_lshlrev_b64 v[0:1], 9, v[8:9]
	v_lshl_add_u64 v[0:1], s[94:95], 0, v[0:1]
	v_lshlrev_b32_e32 v2, 4, v4
	v_lshl_add_u64 v[0:1], v[0:1], 0, v[112:113]
	v_and_b32_e32 v10, 0x70, v2
	v_lshl_add_u64 v[0:1], v[0:1], 0, v[10:11]
	v_add_co_u32_e32 v2, vcc, s30, v0
	v_mul_f32_e32 v22, v3, v14
	s_nop 0
	v_addc_co_u32_e32 v3, vcc, 0, v1, vcc
	v_mov_b64_e32 v[18:19], v[182:183]
	v_mov_b64_e32 v[20:21], v[184:185]
	v_mov_b64_e32 v[4:5], v[186:187]
	v_mov_b64_e32 v[6:7], v[188:189]
	v_add_co_u32_e32 v0, vcc, s31, v0
	v_mul_f32_e32 v16, v12, v14
	s_nop 0
	v_addc_co_u32_e32 v1, vcc, 0, v1, vcc
	v_mov_b64_e32 v[0:1], v[190:191]
	v_mov_b64_e32 v[2:3], v[192:193]
	v_mul_f32_e32 v12, v13, v14
	s_waitcnt vmcnt(2)
	v_lshlrev_b32_e32 v14, 16, v18
	v_and_b32_e32 v15, 0xffff0000, v18
	v_lshlrev_b32_e32 v18, 16, v19
	v_and_b32_e32 v19, 0xffff0000, v19
	v_pk_fma_f32 v[14:15], v[22:23], v[14:15], 0 op_sel_hi:[0,1,0]
	s_waitcnt vmcnt(1)
	v_lshlrev_b32_e32 v24, 16, v4
	v_and_b32_e32 v25, 0xffff0000, v4
	v_pk_fma_f32 v[18:19], v[22:23], v[18:19], 0 op_sel_hi:[0,1,0]
	v_lshlrev_b32_e32 v4, 16, v5
	v_and_b32_e32 v5, 0xffff0000, v5
	v_pk_fma_f32 v[14:15], v[16:17], v[24:25], v[14:15] op_sel_hi:[0,1,1]
	s_waitcnt vmcnt(0)
; DI int tidx() { int t = __builtin_amdgcn_workitem_id_x(); asm volatile("" : "+v"(t)); return t; }
; DI unsigned pk2(float a, float b) { f32x2 v = {a, b}; bf2_t r = __builtin_convertvector(v, bf2_t); return __builtin_bit_cast(unsigned, r); }
; DI float bflo(unsigned u) { return __uint_as_float(u << 16); }
; DI float bfhi(unsigned u) { return __uint_as_float(u & 0xffff0000u); }
; DI void dcombine_unit(const Params& p, int u) {
;     ...
;     const int idx = u * 1024 + e * 512 + tidx(), token = idx >> 5, rem = idx & 31, h = rem >> 3, dc = rem & 7;
;     float ls[3], mx = -1e30f;
; #pragma unroll
;     for (int n = 0; n < 3; ++n) { ls[n] = p.dlse[((size_t)n * NTOK + token) * 4 + h]; mx = fmaxf(mx, ls[n]); }
;     float w[3], ws = 0.f;
; #pragma unroll
;     for (int n = 0; n < 3; ++n) { w[n] = exp2f(ls[n] - mx); ws += w[n]; }
;     const float inv = 1.f / ws;
;     float o[8];
; #pragma unroll
;     for (int i = 0; i < 8; ++i) o[i] = 0.f;
; #pragma unroll
;     for (int n = 0; n < 3; ++n) { const u32x4 d = *(const u32x4*)(p.dpart + ((size_t)n * NTOK + token) * 256 + h * 64 + dc * 8); const float wn = w[n] * inv;
; #pragma unroll
;       for (int i = 0; i < 4; ++i) { o[2 * i] += wn * bflo(d[i]); o[2 * i + 1] += wn * bfhi(d[i]); } }
;     u32x4 r = {pk2(o[0], o[1]), pk2(o[2], o[3]), pk2(o[4], o[5]), pk2(o[6], o[7])};
;     *(u32x4*)(p.Y + (size_t)token * DM + 768 + h * 64 + dc * 8) = r;
	v_lshlrev_b32_e32 v24, 16, v0
	v_and_b32_e32 v25, 0xffff0000, v0
	v_pk_fma_f32 v[4:5], v[16:17], v[4:5], v[18:19] op_sel_hi:[0,1,1]
	v_lshlrev_b32_e32 v0, 16, v1
	v_and_b32_e32 v1, 0xffff0000, v1
	v_pk_fma_f32 v[0:1], v[12:13], v[0:1], v[4:5] op_sel_hi:[0,1,1]
	v_lshlrev_b32_e32 v4, 16, v20
	v_and_b32_e32 v5, 0xffff0000, v20
	v_pk_fma_f32 v[4:5], v[22:23], v[4:5], 0 op_sel_hi:[0,1,0]
	v_lshlrev_b32_e32 v18, 16, v6
	v_and_b32_e32 v19, 0xffff0000, v6
	v_pk_fma_f32 v[4:5], v[16:17], v[18:19], v[4:5] op_sel_hi:[0,1,1]
	v_lshlrev_b32_e32 v18, 16, v2
	v_and_b32_e32 v19, 0xffff0000, v2
	v_pk_fma_f32 v[4:5], v[12:13], v[18:19], v[4:5] op_sel_hi:[0,1,1]
	v_lshlrev_b32_e32 v18, 16, v21
	v_and_b32_e32 v19, 0xffff0000, v21
	v_pk_fma_f32 v[18:19], v[22:23], v[18:19], 0 op_sel_hi:[0,1,0]
	v_lshlrev_b32_e32 v6, 16, v7
	v_and_b32_e32 v7, 0xffff0000, v7
	v_pk_fma_f32 v[6:7], v[16:17], v[6:7], v[18:19] op_sel_hi:[0,1,1]
	v_lshlrev_b32_e32 v2, 16, v3
	v_and_b32_e32 v3, 0xffff0000, v3
	v_pk_fma_f32 v[6:7], v[12:13], v[2:3], v[6:7] op_sel_hi:[0,1,1]
	v_cvt_pk_bf16_f32 v3, v0, v1
	v_lshlrev_b64 v[0:1], 11, v[8:9]
	v_lshl_add_u64 v[0:1], s[40:41], 0, v[0:1]
	v_pk_fma_f32 v[14:15], v[12:13], v[24:25], v[14:15] op_sel_hi:[0,1,1]
	v_lshl_add_u64 v[0:1], v[0:1], 0, v[112:113]
	v_cvt_pk_bf16_f32 v2, v14, v15
	v_cvt_pk_bf16_f32 v4, v4, v5
	v_cvt_pk_bf16_f32 v5, v6, v7
	v_lshl_add_u64 v[0:1], v[0:1], 0, v[10:11]
	global_store_dwordx4 v[0:1], v[2:5], off offset:1536
	v_mov_b32_e32 v15, v113
	s_nop 0
	v_mov_b32_e32 v4, v206
	s_nop 0
	v_add_u32_e32 v0, s0, v4
	v_ashrrev_i32_e32 v12, 5, v0
	v_bfe_u32 v5, v4, 3, 2
	v_ashrrev_i32_e32 v13, 31, v12
	v_lshl_add_u64 v[0:1], v[12:13], 4, s[66:67]
	v_lshlrev_b32_e32 v112, 2, v5
	v_lshl_add_u64 v[0:1], v[0:1], 0, v[112:113]
	v_mov_b32_e32 v6, v212
	v_lshlrev_b32_e32 v112, 7, v5
	s_waitcnt vmcnt(0)
	v_max_f32_e32 v2, v6, v6
	v_max_f32_e32 v7, 0xf149f2ca, v2
	v_add_co_u32_e32 v2, vcc, s27, v0
	s_nop 1
	v_addc_co_u32_e32 v3, vcc, 0, v1, vcc
	v_add_co_u32_e32 v0, vcc, s28, v0
	v_mov_b32_e32 v2, v213
	s_nop 0
	v_addc_co_u32_e32 v1, vcc, 0, v1, vcc
	v_mov_b32_e32 v0, v214
	s_waitcnt vmcnt(0)
	v_max3_f32 v1, v7, v2, v0
	v_sub_f32_e32 v3, v6, v1
	v_cmp_gt_f32_e32 vcc, s29, v3
	v_sub_f32_e32 v2, v2, v1
	v_sub_f32_e32 v0, v0, v1
	v_cndmask_b32_e32 v6, 0, v169, vcc
	v_add_f32_e32 v3, v3, v6
	v_exp_f32_e32 v3, v3
	v_cndmask_b32_e32 v6, 0, v171, vcc
	v_cmp_gt_f32_e32 vcc, s29, v2
	v_ldexp_f32 v6, v3, v6
	s_nop 0
	v_cndmask_b32_e32 v3, 0, v169, vcc
	v_add_f32_e32 v2, v2, v3
	v_cndmask_b32_e32 v3, 0, v171, vcc
	v_cmp_gt_f32_e32 vcc, s29, v0
	v_exp_f32_e32 v2, v2
	s_nop 0
	v_cndmask_b32_e32 v1, 0, v169, vcc
	v_add_f32_e32 v0, v0, v1
	v_exp_f32_e32 v0, v0
	v_ldexp_f32 v10, v2, v3
	v_cndmask_b32_e32 v1, 0, v171, vcc
	v_ldexp_f32 v17, v0, v1
	v_add_f32_e32 v0, v6, v10
	v_add_f32_e32 v0, v17, v0
	v_div_scale_f32 v1, s[0:1], v0, v0, 1.0
	v_rcp_f32_e32 v2, v1
	s_nop 0
	v_fma_f32 v3, -v1, v2, 1.0
	v_fmac_f32_e32 v2, v3, v2
	v_div_scale_f32 v3, vcc, 1.0, v0, 1.0
	v_mul_f32_e32 v7, v3, v2
	v_fma_f32 v8, -v1, v7, v3
	v_fmac_f32_e32 v7, v8, v2
	v_fma_f32 v1, -v1, v7, v3
	v_div_fmas_f32 v1, v1, v2, v7
	v_div_fixup_f32 v19, v1, v0, 1.0
	v_lshlrev_b64 v[0:1], 9, v[12:13]
	v_lshl_add_u64 v[0:1], s[94:95], 0, v[0:1]
	v_lshlrev_b32_e32 v2, 4, v4
	v_lshl_add_u64 v[0:1], v[0:1], 0, v[112:113]
	v_and_b32_e32 v14, 0x70, v2
	v_lshl_add_u64 v[8:9], v[0:1], 0, v[14:15]
	v_add_co_u32_e32 v4, vcc, s30, v8
	v_mov_b64_e32 v[0:1], v[194:195]
	v_mov_b64_e32 v[2:3], v[196:197]
	s_nop 0
	v_addc_co_u32_e32 v5, vcc, 0, v9, vcc
	v_mul_f32_e32 v16, v6, v19
	v_mov_b64_e32 v[4:5], v[198:199]
	v_mov_b64_e32 v[6:7], v[200:201]
	v_add_co_u32_e32 v8, vcc, s31, v8
	v_mul_f32_e32 v18, v10, v19
	s_nop 0
	v_addc_co_u32_e32 v9, vcc, 0, v9, vcc
	v_mov_b64_e32 v[8:9], v[202:203]
	v_mov_b64_e32 v[10:11], v[204:205]
	v_mul_f32_e32 v20, v17, v19
	s_waitcnt vmcnt(2)
	v_lshlrev_b32_e32 v22, 16, v0
	v_and_b32_e32 v23, 0xffff0000, v0
	v_lshlrev_b32_e32 v0, 16, v1
	v_and_b32_e32 v1, 0xffff0000, v1
	s_waitcnt vmcnt(1)
	v_lshlrev_b32_e32 v24, 16, v4
	v_and_b32_e32 v25, 0xffff0000, v4
	v_pk_fma_f32 v[0:1], v[16:17], v[0:1], 0 op_sel_hi:[0,1,0]
	v_lshlrev_b32_e32 v4, 16, v5
	v_and_b32_e32 v5, 0xffff0000, v5
	v_pk_fma_f32 v[0:1], v[18:19], v[4:5], v[0:1] op_sel_hi:[0,1,1]
	s_waitcnt vmcnt(0)
	v_lshlrev_b32_e32 v4, 16, v9
	v_and_b32_e32 v5, 0xffff0000, v9
	v_pk_fma_f32 v[22:23], v[16:17], v[22:23], 0 op_sel_hi:[0,1,0]
	v_pk_fma_f32 v[0:1], v[20:21], v[4:5], v[0:1] op_sel_hi:[0,1,1]
	v_lshlrev_b32_e32 v4, 16, v2
	v_and_b32_e32 v5, 0xffff0000, v2
	v_lshlrev_b32_e32 v2, 16, v3
	v_and_b32_e32 v3, 0xffff0000, v3
	v_pk_fma_f32 v[22:23], v[18:19], v[24:25], v[22:23] op_sel_hi:[0,1,1]
	v_lshlrev_b32_e32 v24, 16, v8
	v_and_b32_e32 v25, 0xffff0000, v8
	v_lshlrev_b32_e32 v8, 16, v6
	v_and_b32_e32 v9, 0xffff0000, v6
	v_pk_fma_f32 v[2:3], v[16:17], v[2:3], 0 op_sel_hi:[0,1,0]
	v_lshlrev_b32_e32 v6, 16, v7
	v_and_b32_e32 v7, 0xffff0000, v7
	v_pk_fma_f32 v[2:3], v[18:19], v[6:7], v[2:3] op_sel_hi:[0,1,1]
	v_lshlrev_b32_e32 v6, 16, v11
	v_and_b32_e32 v7, 0xffff0000, v11
	v_pk_fma_f32 v[4:5], v[16:17], v[4:5], 0 op_sel_hi:[0,1,0]
	v_pk_fma_f32 v[6:7], v[20:21], v[6:7], v[2:3] op_sel_hi:[0,1,1]
	v_cvt_pk_bf16_f32 v3, v0, v1
	v_lshlrev_b64 v[0:1], 11, v[12:13]
	v_pk_fma_f32 v[4:5], v[18:19], v[8:9], v[4:5] op_sel_hi:[0,1,1]
	v_lshlrev_b32_e32 v8, 16, v10
	v_and_b32_e32 v9, 0xffff0000, v10
	v_lshl_add_u64 v[0:1], s[40:41], 0, v[0:1]
	v_pk_fma_f32 v[22:23], v[20:21], v[24:25], v[22:23] op_sel_hi:[0,1,1]
	v_pk_fma_f32 v[4:5], v[20:21], v[8:9], v[4:5] op_sel_hi:[0,1,1]
	v_lshl_add_u64 v[0:1], v[0:1], 0, v[112:113]
	v_cvt_pk_bf16_f32 v2, v22, v23
	v_cvt_pk_bf16_f32 v4, v4, v5
	v_cvt_pk_bf16_f32 v5, v6, v7
	v_lshl_add_u64 v[0:1], v[0:1], 0, v[14:15]
	global_store_dwordx4 v[0:1], v[2:5], off offset:1536
	s_branch .LBB0_574

; DI int tidx() { int t = __builtin_amdgcn_workitem_id_x(); asm volatile("" : "+v"(t)); return t; }
; DI float bflo(unsigned u) { return __uint_as_float(u << 16); }
; DI float bfhi(unsigned u) { return __uint_as_float(u & 0xffff0000u); }
; DI void dcombine_unit(const Params& p, int u) {
;     ...
;     const int idx = u * 1024 + e * 512 + tidx(), token = idx >> 5, rem = idx & 31, h = rem >> 3, dc = rem & 7;
;     float ls[3], mx = -1e30f;
; #pragma unroll
;     for (int n = 0; n < 3; ++n) { ls[n] = p.dlse[((size_t)n * NTOK + token) * 4 + h]; mx = fmaxf(mx, ls[n]); }
;     float w[3], ws = 0.f;
; #pragma unroll
;     for (int n = 0; n < 3; ++n) { w[n] = exp2f(ls[n] - mx); ws += w[n]; }
;     const float inv = 1.f / ws;
;     float o[8];
; #pragma unroll
;     for (int i = 0; i < 8; ++i) o[i] = 0.f;
; #pragma unroll
;     for (int n = 0; n < 3; ++n) { const u32x4 d = *(const u32x4*)(p.dpart + ((size_t)n * NTOK + token) * 256 + h * 64 + dc * 8); const float wn = w[n] * inv;
; #pragma unroll
;       for (int i = 0; i < 4; ++i) { o[2 * i] += wn * bflo(d[i]); o[2 * i + 1] += wn * bfhi(d[i]); } }
.LBB0_1619:
	s_andn2_b64 vcc, exec, s[0:1]
	s_cbranch_vccnz .LBB0_1551
	s_lshl_b32 s0, s90, 10
	s_add_i32 s1, s0, 0xffe00000
	v_mov_b32_e32 v4, v206
	v_readlane_b32 s52, v252, 17
	v_add_u32_e32 v0, s1, v4
	v_ashrrev_i32_e32 v8, 5, v0
	v_bfe_u32 v5, v4, 3, 2
	v_ashrrev_i32_e32 v9, 31, v8
	v_readlane_b32 s66, v252, 31
	v_readlane_b32 s67, v252, 32
	v_lshlrev_b32_e32 v112, 2, v5
	s_mov_b64 s[16:17], s[88:89]
	v_lshl_add_u64 v[0:1], v[8:9], 4, s[66:67]
	v_lshl_add_u64 v[0:1], v[0:1], 0, v[112:113]
	global_load_dword v6, v[0:1], off
	v_lshlrev_b64 v[216:217], 9, v[8:9]
	v_lshl_add_u64 v[216:217], s[88:89], 0, v[216:217]
	v_lshlrev_b32_e32 v218, 7, v5
	v_lshlrev_b32_e32 v219, 4, v4
	v_and_b32_e32 v219, 0x70, v219
	v_add_u32_e32 v218, v218, v219
	v_mov_b32_e32 v219, 0
	v_lshl_add_u64 v[216:217], v[216:217], 0, v[218:219]
	v_mov_b32_e32 v218, s82
	v_lshl_add_u64 v[220:221], v[216:217], 0, v[218:219]
	v_mov_b32_e32 v218, s83
	v_lshl_add_u64 v[222:223], v[216:217], 0, v[218:219]
	global_load_dwordx4 v[182:185], v[216:217], off
	global_load_dwordx4 v[186:189], v[220:221], off
	global_load_dwordx4 v[190:193], v[222:223], off
	v_mov_b32_e32 v218, 0x2000
	v_lshl_add_u64 v[216:217], v[216:217], 0, v[218:219]
	v_lshl_add_u64 v[220:221], v[220:221], 0, v[218:219]
	v_lshl_add_u64 v[222:223], v[222:223], 0, v[218:219]
	global_load_dwordx4 v[194:197], v[216:217], off
	global_load_dwordx4 v[198:201], v[220:221], off
	global_load_dwordx4 v[202:205], v[222:223], off
	v_mov_b32_e32 v218, s79
	v_lshl_add_u64 v[224:225], v[0:1], 0, v[218:219]
	v_mov_b32_e32 v218, s80
	v_lshl_add_u64 v[226:227], v[0:1], 0, v[218:219]
	global_load_dword v210, v[224:225], off
	global_load_dword v211, v[226:227], off
	global_load_dword v212, v[0:1], off offset:256
	global_load_dword v213, v[224:225], off offset:256
	global_load_dword v214, v[226:227], off offset:256
	v_lshlrev_b32_e32 v112, 7, v5
	v_mov_b32_e32 v11, v113
	v_readlane_b32 s8, v252, 36
	v_readlane_b32 s12, v252, 40
	v_readlane_b32 s13, v252, 41
	s_add_i32 s0, s0, 0xffe00200
	v_readlane_b32 s53, v252, 18
	v_readlane_b32 s54, v252, 19
	v_readlane_b32 s55, v252, 20
	v_readlane_b32 s56, v252, 21
	v_readlane_b32 s57, v252, 22
	v_readlane_b32 s58, v252, 23
	v_readlane_b32 s59, v252, 24
	v_readlane_b32 s60, v252, 25
	v_readlane_b32 s61, v252, 26
	v_readlane_b32 s62, v252, 27
	v_readlane_b32 s63, v252, 28
	v_readlane_b32 s64, v252, 29
	v_readlane_b32 s65, v252, 30
	v_readlane_b32 s9, v252, 37
	v_readlane_b32 s10, v252, 38
	v_readlane_b32 s11, v252, 39
	v_readlane_b32 s14, v252, 42
	v_readlane_b32 s15, v252, 43
	s_waitcnt vmcnt(0)
	v_max_f32_e32 v2, v6, v6
	v_max_f32_e32 v7, 0xf149f2ca, v2
	v_add_co_u32_e32 v2, vcc, s79, v0
	s_nop 1
	v_addc_co_u32_e32 v3, vcc, 0, v1, vcc
	v_add_co_u32_e32 v0, vcc, s80, v0
	v_mov_b32_e32 v2, v210
	s_nop 0
	v_addc_co_u32_e32 v1, vcc, 0, v1, vcc
	v_mov_b32_e32 v0, v211
	s_waitcnt vmcnt(0)
	v_max3_f32 v1, v7, v2, v0
	v_sub_f32_e32 v3, v6, v1
	v_cmp_gt_f32_e32 vcc, s81, v3
	v_sub_f32_e32 v2, v2, v1
	v_sub_f32_e32 v0, v0, v1
	v_cndmask_b32_e32 v6, 0, v169, vcc
	v_add_f32_e32 v3, v3, v6
	v_exp_f32_e32 v3, v3
	v_cndmask_b32_e32 v6, 0, v171, vcc
	v_cmp_gt_f32_e32 vcc, s81, v2
	v_ldexp_f32 v3, v3, v6
	s_nop 0
	v_cndmask_b32_e32 v6, 0, v169, vcc
	v_add_f32_e32 v2, v2, v6
	v_cndmask_b32_e32 v6, 0, v171, vcc
	v_cmp_gt_f32_e32 vcc, s81, v0
	v_exp_f32_e32 v2, v2
	s_nop 0
	v_cndmask_b32_e32 v1, 0, v169, vcc
	v_add_f32_e32 v0, v0, v1
	v_exp_f32_e32 v0, v0
	v_ldexp_f32 v12, v2, v6
	v_cndmask_b32_e32 v1, 0, v171, vcc
	v_ldexp_f32 v13, v0, v1
	v_add_f32_e32 v0, v3, v12
	v_add_f32_e32 v0, v13, v0
	v_div_scale_f32 v1, s[50:51], v0, v0, 1.0
	v_rcp_f32_e32 v2, v1
	s_nop 0
	v_fma_f32 v6, -v1, v2, 1.0
	v_fmac_f32_e32 v2, v6, v2
	v_div_scale_f32 v6, vcc, 1.0, v0, 1.0
	v_mul_f32_e32 v7, v6, v2
	v_fma_f32 v10, -v1, v7, v6
	v_fmac_f32_e32 v7, v10, v2
	v_fma_f32 v1, -v1, v7, v6
	v_div_fmas_f32 v1, v1, v2, v7
	v_div_fixup_f32 v14, v1, v0, 1.0
	v_lshlrev_b64 v[0:1], 9, v[8:9]
	v_lshl_add_u64 v[0:1], s[16:17], 0, v[0:1]
	v_lshlrev_b32_e32 v2, 4, v4
	v_lshl_add_u64 v[0:1], v[0:1], 0, v[112:113]
	v_and_b32_e32 v10, 0x70, v2
	v_lshl_add_u64 v[0:1], v[0:1], 0, v[10:11]
	v_add_co_u32_e32 v2, vcc, s82, v0
	v_mul_f32_e32 v22, v3, v14
	s_nop 0
	v_addc_co_u32_e32 v3, vcc, 0, v1, vcc
	v_mov_b64_e32 v[18:19], v[182:183]
	v_mov_b64_e32 v[20:21], v[184:185]
	v_mov_b64_e32 v[4:5], v[186:187]
	v_mov_b64_e32 v[6:7], v[188:189]
	v_add_co_u32_e32 v0, vcc, s83, v0
	v_mul_f32_e32 v16, v12, v14
	s_nop 0
	v_addc_co_u32_e32 v1, vcc, 0, v1, vcc
	v_mov_b64_e32 v[0:1], v[190:191]
	v_mov_b64_e32 v[2:3], v[192:193]
	v_mul_f32_e32 v12, v13, v14
	s_waitcnt vmcnt(2)
	v_lshlrev_b32_e32 v14, 16, v18
	v_and_b32_e32 v15, 0xffff0000, v18
	v_lshlrev_b32_e32 v18, 16, v19
	v_and_b32_e32 v19, 0xffff0000, v19
	v_pk_fma_f32 v[14:15], v[22:23], v[14:15], 0 op_sel_hi:[0,1,0]
	s_waitcnt vmcnt(1)
	v_lshlrev_b32_e32 v24, 16, v4
	v_and_b32_e32 v25, 0xffff0000, v4
	v_pk_fma_f32 v[18:19], v[22:23], v[18:19], 0 op_sel_hi:[0,1,0]
	v_lshlrev_b32_e32 v4, 16, v5
	v_and_b32_e32 v5, 0xffff0000, v5
	v_pk_fma_f32 v[14:15], v[16:17], v[24:25], v[14:15] op_sel_hi:[0,1,1]
	s_waitcnt vmcnt(0)
; DI int tidx() { int t = __builtin_amdgcn_workitem_id_x(); asm volatile("" : "+v"(t)); return t; }
; DI unsigned pk2(float a, float b) { f32x2 v = {a, b}; bf2_t r = __builtin_convertvector(v, bf2_t); return __builtin_bit_cast(unsigned, r); }
; DI float bflo(unsigned u) { return __uint_as_float(u << 16); }
; DI float bfhi(unsigned u) { return __uint_as_float(u & 0xffff0000u); }
; DI void dcombine_unit(const Params& p, int u) {
;     ...
;     const int idx = u * 1024 + e * 512 + tidx(), token = idx >> 5, rem = idx & 31, h = rem >> 3, dc = rem & 7;
;     float ls[3], mx = -1e30f;
; #pragma unroll
;     for (int n = 0; n < 3; ++n) { ls[n] = p.dlse[((size_t)n * NTOK + token) * 4 + h]; mx = fmaxf(mx, ls[n]); }
;     float w[3], ws = 0.f;
; #pragma unroll
;     for (int n = 0; n < 3; ++n) { w[n] = exp2f(ls[n] - mx); ws += w[n]; }
;     const float inv = 1.f / ws;
;     float o[8];
; #pragma unroll
;     for (int i = 0; i < 8; ++i) o[i] = 0.f;
; #pragma unroll
;     for (int n = 0; n < 3; ++n) { const u32x4 d = *(const u32x4*)(p.dpart + ((size_t)n * NTOK + token) * 256 + h * 64 + dc * 8); const float wn = w[n] * inv;
; #pragma unroll
;       for (int i = 0; i < 4; ++i) { o[2 * i] += wn * bflo(d[i]); o[2 * i + 1] += wn * bfhi(d[i]); } }
;     u32x4 r = {pk2(o[0], o[1]), pk2(o[2], o[3]), pk2(o[4], o[5]), pk2(o[6], o[7])};
;     *(u32x4*)(p.Y + (size_t)token * DM + 768 + h * 64 + dc * 8) = r;
	v_lshlrev_b32_e32 v24, 16, v0
	v_and_b32_e32 v25, 0xffff0000, v0
	v_pk_fma_f32 v[4:5], v[16:17], v[4:5], v[18:19] op_sel_hi:[0,1,1]
	v_lshlrev_b32_e32 v0, 16, v1
	v_and_b32_e32 v1, 0xffff0000, v1
	v_pk_fma_f32 v[0:1], v[12:13], v[0:1], v[4:5] op_sel_hi:[0,1,1]
	v_lshlrev_b32_e32 v4, 16, v20
	v_and_b32_e32 v5, 0xffff0000, v20
	v_pk_fma_f32 v[4:5], v[22:23], v[4:5], 0 op_sel_hi:[0,1,0]
	v_lshlrev_b32_e32 v18, 16, v6
	v_and_b32_e32 v19, 0xffff0000, v6
	v_pk_fma_f32 v[4:5], v[16:17], v[18:19], v[4:5] op_sel_hi:[0,1,1]
	v_lshlrev_b32_e32 v18, 16, v2
	v_and_b32_e32 v19, 0xffff0000, v2
	v_pk_fma_f32 v[4:5], v[12:13], v[18:19], v[4:5] op_sel_hi:[0,1,1]
	v_lshlrev_b32_e32 v18, 16, v21
	v_and_b32_e32 v19, 0xffff0000, v21
	v_pk_fma_f32 v[18:19], v[22:23], v[18:19], 0 op_sel_hi:[0,1,0]
	v_lshlrev_b32_e32 v6, 16, v7
	v_and_b32_e32 v7, 0xffff0000, v7
	v_pk_fma_f32 v[6:7], v[16:17], v[6:7], v[18:19] op_sel_hi:[0,1,1]
	v_lshlrev_b32_e32 v2, 16, v3
	v_and_b32_e32 v3, 0xffff0000, v3
	v_pk_fma_f32 v[6:7], v[12:13], v[2:3], v[6:7] op_sel_hi:[0,1,1]
	v_cvt_pk_bf16_f32 v3, v0, v1
	v_lshlrev_b64 v[0:1], 11, v[8:9]
	v_lshl_add_u64 v[0:1], s[12:13], 0, v[0:1]
	v_pk_fma_f32 v[14:15], v[12:13], v[24:25], v[14:15] op_sel_hi:[0,1,1]
	v_lshl_add_u64 v[0:1], v[0:1], 0, v[112:113]
	v_cvt_pk_bf16_f32 v2, v14, v15
	v_cvt_pk_bf16_f32 v4, v4, v5
	v_cvt_pk_bf16_f32 v5, v6, v7
	v_lshl_add_u64 v[0:1], v[0:1], 0, v[10:11]
	global_store_dwordx4 v[0:1], v[2:5], off offset:1536
	v_mov_b32_e32 v15, v113
	s_nop 0
	v_mov_b32_e32 v4, v206
	s_nop 0
	v_add_u32_e32 v0, s0, v4
	v_ashrrev_i32_e32 v12, 5, v0
	v_bfe_u32 v5, v4, 3, 2
	v_ashrrev_i32_e32 v13, 31, v12
	v_lshl_add_u64 v[0:1], v[12:13], 4, s[66:67]
	v_lshlrev_b32_e32 v112, 2, v5
	v_lshl_add_u64 v[0:1], v[0:1], 0, v[112:113]
	v_mov_b32_e32 v6, v212
	v_lshlrev_b32_e32 v112, 7, v5
	s_waitcnt vmcnt(0)
	v_max_f32_e32 v2, v6, v6
	v_max_f32_e32 v7, 0xf149f2ca, v2
	v_add_co_u32_e32 v2, vcc, s79, v0
	s_nop 1
	v_addc_co_u32_e32 v3, vcc, 0, v1, vcc
	v_add_co_u32_e32 v0, vcc, s80, v0
	v_mov_b32_e32 v2, v213
	s_nop 0
	v_addc_co_u32_e32 v1, vcc, 0, v1, vcc
	v_mov_b32_e32 v0, v214
	s_waitcnt vmcnt(0)
	v_max3_f32 v1, v7, v2, v0
	v_sub_f32_e32 v3, v6, v1
	v_cmp_gt_f32_e32 vcc, s81, v3
	v_sub_f32_e32 v2, v2, v1
	v_sub_f32_e32 v0, v0, v1
	v_cndmask_b32_e32 v6, 0, v169, vcc
	v_add_f32_e32 v3, v3, v6
	v_exp_f32_e32 v3, v3
	v_cndmask_b32_e32 v6, 0, v171, vcc
	v_cmp_gt_f32_e32 vcc, s81, v2
	v_ldexp_f32 v6, v3, v6
	s_nop 0
	v_cndmask_b32_e32 v3, 0, v169, vcc
	v_add_f32_e32 v2, v2, v3
	v_cndmask_b32_e32 v3, 0, v171, vcc
	v_cmp_gt_f32_e32 vcc, s81, v0
	v_exp_f32_e32 v2, v2
	s_nop 0
	v_cndmask_b32_e32 v1, 0, v169, vcc
	v_add_f32_e32 v0, v0, v1
	v_exp_f32_e32 v0, v0
	v_ldexp_f32 v10, v2, v3
	v_cndmask_b32_e32 v1, 0, v171, vcc
	v_ldexp_f32 v17, v0, v1
	v_add_f32_e32 v0, v6, v10
	v_add_f32_e32 v0, v17, v0
	v_div_scale_f32 v1, s[0:1], v0, v0, 1.0
	v_rcp_f32_e32 v2, v1
	s_nop 0
	v_fma_f32 v3, -v1, v2, 1.0
	v_fmac_f32_e32 v2, v3, v2
	v_div_scale_f32 v3, vcc, 1.0, v0, 1.0
	v_mul_f32_e32 v7, v3, v2
	v_fma_f32 v8, -v1, v7, v3
	v_fmac_f32_e32 v7, v8, v2
	v_fma_f32 v1, -v1, v7, v3
	v_div_fmas_f32 v1, v1, v2, v7
	v_div_fixup_f32 v19, v1, v0, 1.0
	v_lshlrev_b64 v[0:1], 9, v[12:13]
	v_lshl_add_u64 v[0:1], s[16:17], 0, v[0:1]
	v_lshlrev_b32_e32 v2, 4, v4
	v_lshl_add_u64 v[0:1], v[0:1], 0, v[112:113]
	v_and_b32_e32 v14, 0x70, v2
	v_lshl_add_u64 v[8:9], v[0:1], 0, v[14:15]
	v_add_co_u32_e32 v4, vcc, s82, v8
	v_mov_b64_e32 v[0:1], v[194:195]
	v_mov_b64_e32 v[2:3], v[196:197]
	s_nop 0
	v_addc_co_u32_e32 v5, vcc, 0, v9, vcc
	v_mul_f32_e32 v16, v6, v19
	v_mov_b64_e32 v[4:5], v[198:199]
	v_mov_b64_e32 v[6:7], v[200:201]
	v_add_co_u32_e32 v8, vcc, s83, v8
	v_mul_f32_e32 v18, v10, v19
	s_nop 0
	v_addc_co_u32_e32 v9, vcc, 0, v9, vcc
	v_mov_b64_e32 v[8:9], v[202:203]
	v_mov_b64_e32 v[10:11], v[204:205]
	v_mul_f32_e32 v20, v17, v19
	s_waitcnt vmcnt(2)
	v_lshlrev_b32_e32 v22, 16, v0
	v_and_b32_e32 v23, 0xffff0000, v0
	v_lshlrev_b32_e32 v0, 16, v1
	v_and_b32_e32 v1, 0xffff0000, v1
	s_waitcnt vmcnt(1)
	v_lshlrev_b32_e32 v24, 16, v4
	v_and_b32_e32 v25, 0xffff0000, v4
	v_pk_fma_f32 v[0:1], v[16:17], v[0:1], 0 op_sel_hi:[0,1,0]
	v_lshlrev_b32_e32 v4, 16, v5
	v_and_b32_e32 v5, 0xffff0000, v5
	v_pk_fma_f32 v[0:1], v[18:19], v[4:5], v[0:1] op_sel_hi:[0,1,1]
	s_waitcnt vmcnt(0)
	v_lshlrev_b32_e32 v4, 16, v9
	v_and_b32_e32 v5, 0xffff0000, v9
	v_pk_fma_f32 v[22:23], v[16:17], v[22:23], 0 op_sel_hi:[0,1,0]
	v_pk_fma_f32 v[0:1], v[20:21], v[4:5], v[0:1] op_sel_hi:[0,1,1]
	v_lshlrev_b32_e32 v4, 16, v2
	v_and_b32_e32 v5, 0xffff0000, v2
	v_lshlrev_b32_e32 v2, 16, v3
	v_and_b32_e32 v3, 0xffff0000, v3
	v_pk_fma_f32 v[22:23], v[18:19], v[24:25], v[22:23] op_sel_hi:[0,1,1]
	v_lshlrev_b32_e32 v24, 16, v8
	v_and_b32_e32 v25, 0xffff0000, v8
	v_lshlrev_b32_e32 v8, 16, v6
	v_and_b32_e32 v9, 0xffff0000, v6
	v_pk_fma_f32 v[2:3], v[16:17], v[2:3], 0 op_sel_hi:[0,1,0]
	v_lshlrev_b32_e32 v6, 16, v7
	v_and_b32_e32 v7, 0xffff0000, v7
	v_pk_fma_f32 v[2:3], v[18:19], v[6:7], v[2:3] op_sel_hi:[0,1,1]
	v_lshlrev_b32_e32 v6, 16, v11
	v_and_b32_e32 v7, 0xffff0000, v11
	v_pk_fma_f32 v[4:5], v[16:17], v[4:5], 0 op_sel_hi:[0,1,0]
	v_pk_fma_f32 v[6:7], v[20:21], v[6:7], v[2:3] op_sel_hi:[0,1,1]
	v_cvt_pk_bf16_f32 v3, v0, v1
	v_lshlrev_b64 v[0:1], 11, v[12:13]
	v_pk_fma_f32 v[4:5], v[18:19], v[8:9], v[4:5] op_sel_hi:[0,1,1]
	v_lshlrev_b32_e32 v8, 16, v10
	v_and_b32_e32 v9, 0xffff0000, v10
	v_lshl_add_u64 v[0:1], s[12:13], 0, v[0:1]
	v_pk_fma_f32 v[22:23], v[20:21], v[24:25], v[22:23] op_sel_hi:[0,1,1]
	v_pk_fma_f32 v[4:5], v[20:21], v[8:9], v[4:5] op_sel_hi:[0,1,1]
	v_lshl_add_u64 v[0:1], v[0:1], 0, v[112:113]
	v_cvt_pk_bf16_f32 v2, v22, v23
	v_cvt_pk_bf16_f32 v4, v4, v5
	v_cvt_pk_bf16_f32 v5, v6, v7
	v_lshl_add_u64 v[0:1], v[0:1], 0, v[14:15]
	global_store_dwordx4 v[0:1], v[2:5], off offset:1536
	s_branch .LBB0_1551
